# strategy 7.12: attention tile-loop exit test - the 8 per-wave alive flags read with two ds_read_b128 + v_or3 + one readfirstlane instead of 7 serialized LDS round trips
# speedup vs baseline: 1.0064x; 1.0064x over previous
; #define VMW(n) asm volatile("s_waitcnt vmcnt(" #n ")" ::: "memory")
; #define BAR() do { asm volatile("s_waitcnt lgkmcnt(0)" ::: "memory"); __builtin_amdgcn_s_barrier(); asm volatile("" ::: "memory"); } while (0)
; template <bool SBK>
; __device__ __forceinline__ void attn_unit(const Args& a, int l, LAS char* lds, int b, int h8, int P0, int orow0, int nvalid) {
;     ...
;         if constexpr (SBK) { const bool alive = __any(R > SB_EXIT); if (lane == 0) flag[(t & 1) * 8 + wid] = alive ? 1u : 0u; }
;         else { const float cl_ = more ? cm_l[kb - 1] : 0.f;
;                const bool alive = __any(qbound - cl_ - m_reg > FOX_EXIT); if (lane == 0) flag[(t & 1) * 8 + wid] = alive ? 1u : 0u; }
;         if (t + 2 < NT) VMW(4); else VMW(0);
;         BAR();
;         { unsigned any_ = 0u;
; #pragma unroll
;  for (int w_ = 0; w_ < 8; ++w_) any_ |= flag[(t & 1) * 8 + w_]; if (!any_) break; }
;         if (++t == NT) break;
.LBB0_455:
	s_lshl_b32 s0, s2, 5
	s_and_b32 s0, s0, 32
	s_add_i32 s0, s0, 0
	s_add_i32 s0, s0, 0x18800
	s_waitcnt lgkmcnt(0)
	s_barrier
	v_mov_b32_e32 v0, s0
	ds_read_b128 v[2:5], v0
	ds_read_b128 v[6:9], v0 offset:16
	s_waitcnt lgkmcnt(0)
	v_or3_b32 v2, v2, v3, v4
	v_or3_b32 v6, v6, v7, v8
	v_or3_b32 v2, v2, v5, v6
	v_or_b32_e32 v2, v2, v9
	s_nop 0
	v_readfirstlane_b32 s0, v2
	s_cmp_lg_u32 s0, 0
	s_cselect_b64 s[0:1], -1, 0
	s_cmp_lg_u32 s2, 3
	s_cselect_b64 s[4:5], -1, 0
	s_cmp_lg_u64 s[0:1], 0
	s_addc_u32 s2, s2, 0
	s_and_b64 s[0:1], s[4:5], s[0:1]
	s_and_b64 vcc, exec, s[0:1]
	s_cbranch_vccz .LBB0_461
	s_mov_b32 s1, s6
	s_branch .LBB0_449

; #define VMW(n) asm volatile("s_waitcnt vmcnt(" #n ")" ::: "memory")
; #define BAR() do { asm volatile("s_waitcnt lgkmcnt(0)" ::: "memory"); __builtin_amdgcn_s_barrier(); asm volatile("" ::: "memory"); } while (0)
; template <bool SBK>
; __device__ __forceinline__ void attn_unit(const Args& a, int l, LAS char* lds, int b, int h8, int P0, int orow0, int nvalid) {
;     ...
;         if constexpr (SBK) { const bool alive = __any(R > SB_EXIT); if (lane == 0) flag[(t & 1) * 8 + wid] = alive ? 1u : 0u; }
;         else { const float cl_ = more ? cm_l[kb - 1] : 0.f;
;                const bool alive = __any(qbound - cl_ - m_reg > FOX_EXIT); if (lane == 0) flag[(t & 1) * 8 + wid] = alive ? 1u : 0u; }
;         if (t + 2 < NT) VMW(4); else VMW(0);
;         BAR();
;         { unsigned any_ = 0u;
; #pragma unroll
;  for (int w_ = 0; w_ < 8; ++w_) any_ |= flag[(t & 1) * 8 + w_]; if (!any_) break; }
;         if (++t == NT) break;
.LBB0_509:
	s_lshl_b32 s0, s2, 5
	s_and_b32 s0, s0, 32
	s_add_i32 s0, s0, 0
	s_add_i32 s0, s0, 0x18800
	s_waitcnt lgkmcnt(0)
	s_barrier
	v_mov_b32_e32 v0, s0
	ds_read_b128 v[2:5], v0
	ds_read_b128 v[6:9], v0 offset:16
	s_waitcnt lgkmcnt(0)
	v_or3_b32 v2, v2, v3, v4
	v_or3_b32 v6, v6, v7, v8
	v_or3_b32 v2, v2, v5, v6
	v_or_b32_e32 v2, v2, v9
	s_nop 0
	v_readfirstlane_b32 s4, v2
	s_cmp_lg_u32 s4, 0
	s_cselect_b64 s[0:1], -1, 0
	s_cmp_eq_u32 s4, 0
	s_cselect_b64 s[4:5], -1, 0
	s_cmp_eq_u32 s8, s2
	s_cselect_b64 s[26:27], -1, 0
	s_or_b64 s[4:5], s[4:5], s[26:27]
	s_cmp_lg_u64 s[0:1], 0
	s_addc_u32 s2, s2, 0
	s_andn2_b64 vcc, exec, s[4:5]
	s_cbranch_vccz .LBB0_515
	s_mov_b32 s1, s6
	s_branch .LBB0_503

; #define VMW(n) asm volatile("s_waitcnt vmcnt(" #n ")" ::: "memory")
; #define BAR() do { asm volatile("s_waitcnt lgkmcnt(0)" ::: "memory"); __builtin_amdgcn_s_barrier(); asm volatile("" ::: "memory"); } while (0)
; template <bool SBK>
; __device__ __forceinline__ void attn_unit(const Args& a, int l, LAS char* lds, int b, int h8, int P0, int orow0, int nvalid) {
;     ...
;         if constexpr (SBK) { const bool alive = __any(R > SB_EXIT); if (lane == 0) flag[(t & 1) * 8 + wid] = alive ? 1u : 0u; }
;         else { const float cl_ = more ? cm_l[kb - 1] : 0.f;
;                const bool alive = __any(qbound - cl_ - m_reg > FOX_EXIT); if (lane == 0) flag[(t & 1) * 8 + wid] = alive ? 1u : 0u; }
;         if (t + 2 < NT) VMW(4); else VMW(0);
;         BAR();
;         { unsigned any_ = 0u;
; #pragma unroll
;  for (int w_ = 0; w_ < 8; ++w_) any_ |= flag[(t & 1) * 8 + w_]; if (!any_) break; }
;         if (++t == NT) break;
.LBB0_583:
	s_lshl_b32 s0, s23, 5
	s_and_b32 s0, s0, 32
	s_add_i32 s0, s0, 0
	s_add_i32 s0, s0, 0x18800
	s_waitcnt lgkmcnt(0)
	s_barrier
	v_mov_b32_e32 v0, s0
	ds_read_b128 v[2:5], v0
	ds_read_b128 v[6:9], v0 offset:16
	s_waitcnt lgkmcnt(0)
	v_or3_b32 v2, v2, v3, v4
	v_or3_b32 v6, v6, v7, v8
	v_or3_b32 v2, v2, v5, v6
	v_or_b32_e32 v2, v2, v9
	s_nop 0
	v_readfirstlane_b32 s4, v2
	s_cmp_lg_u32 s4, 0
	s_cselect_b64 s[0:1], -1, 0
	s_cmp_eq_u32 s4, 0
	s_cselect_b64 s[4:5], -1, 0
	s_cmp_eq_u32 s7, s23
	s_cselect_b64 s[40:41], -1, 0
	s_or_b64 s[4:5], s[4:5], s[40:41]
	s_cmp_lg_u64 s[0:1], 0
	s_addc_u32 s23, s23, 0
	s_andn2_b64 vcc, exec, s[4:5]
	s_cbranch_vccz .LBB0_587
	s_mov_b32 s4, s26
	v_mov_b32_e32 v183, v96
	s_branch .LBB0_567

; #define VMW(n) asm volatile("s_waitcnt vmcnt(" #n ")" ::: "memory")
; #define BAR() do { asm volatile("s_waitcnt lgkmcnt(0)" ::: "memory"); __builtin_amdgcn_s_barrier(); asm volatile("" ::: "memory"); } while (0)
; template <bool SBK>
; __device__ __forceinline__ void attn_unit(const Args& a, int l, LAS char* lds, int b, int h8, int P0, int orow0, int nvalid) {
;     ...
;         if constexpr (SBK) { const bool alive = __any(R > SB_EXIT); if (lane == 0) flag[(t & 1) * 8 + wid] = alive ? 1u : 0u; }
;         else { const float cl_ = more ? cm_l[kb - 1] : 0.f;
;                const bool alive = __any(qbound - cl_ - m_reg > FOX_EXIT); if (lane == 0) flag[(t & 1) * 8 + wid] = alive ? 1u : 0u; }
;         if (t + 2 < NT) VMW(4); else VMW(0);
;         BAR();
;         { unsigned any_ = 0u;
; #pragma unroll
;  for (int w_ = 0; w_ < 8; ++w_) any_ |= flag[(t & 1) * 8 + w_]; if (!any_) break; }
;         if (++t == NT) break;
.LBB0_718:
	s_lshl_b32 s0, s7, 5
	s_and_b32 s0, s0, 32
	s_add_i32 s0, s0, 0
	s_add_i32 s0, s0, 0x18800
	s_waitcnt lgkmcnt(0)
	s_barrier
	v_mov_b32_e32 v0, s0
	ds_read_b128 v[2:5], v0
	ds_read_b128 v[6:9], v0 offset:16
	s_waitcnt lgkmcnt(0)
	v_or3_b32 v2, v2, v3, v4
	v_or3_b32 v6, v6, v7, v8
	v_or3_b32 v2, v2, v5, v6
	v_or_b32_e32 v2, v2, v9
	s_nop 0
	v_readfirstlane_b32 s0, v2
	s_cmp_lg_u32 s0, 0
	s_cselect_b64 s[0:1], -1, 0
	s_cmp_lg_u32 s7, 3
	s_cselect_b64 s[22:23], -1, 0
	s_cmp_lg_u64 s[0:1], 0
	s_addc_u32 s7, s7, 0
	s_and_b64 s[0:1], s[22:23], s[0:1]
	s_and_b64 vcc, exec, s[0:1]
	s_cbranch_vccz .LBB0_722
	s_mov_b32 s22, s8
	v_mov_b32_e32 v183, v96
	s_branch .LBB0_702
